# P0 adaLN modulation GEMV: next k-step's four weight rows prefetched (global loads) while the current step computes
# speedup vs baseline: 1.0004x; 1.0004x over previous
.LBB0_21:
	v_and_b32_e32 v4, 0x3ff, v3
	v_lshlrev_b32_e32 v86, 2, v4
	v_lshl_add_u64 v[4:5], s[6:7], 0, v[86:87]
	v_cmp_gt_u32_e32 vcc, s12, v3
	s_nop 1
	v_cndmask_b32_e32 v5, v5, v1, vcc
	v_cndmask_b32_e32 v4, v4, v0, vcc
	flat_load_dword v4, v[4:5]
	v_add_u32_e32 v5, 0x200, v3
	v_cmp_lt_u32_e32 vcc, s13, v3
	v_mov_b32_e32 v3, v5
	s_or_b64 s[8:9], vcc, s[8:9]
	v_lshl_add_u64 v[0:1], v[0:1], 0, s[0:1]
	s_waitcnt vmcnt(0) lgkmcnt(0)
	v_mul_f32_e32 v5, 0xbfb8aa3b, v4
	v_exp_f32_e32 v5, v5
	s_nop 0
	v_add_f32_e32 v5, 1.0, v5
	v_div_scale_f32 v6, s[24:25], v5, v5, v4
	v_rcp_f32_e32 v7, v6
	v_div_scale_f32 v8, vcc, v4, v5, v4
	v_fma_f32 v9, -v6, v7, 1.0
	v_fmac_f32_e32 v7, v9, v7
	v_mul_f32_e32 v9, v8, v7
	v_fma_f32 v10, -v6, v9, v8
	v_fmac_f32_e32 v9, v10, v7
	v_fma_f32 v6, -v6, v9, v8
	v_div_fmas_f32 v6, v6, v7, v9
	v_div_fixup_f32 v4, v6, v5, v4
	ds_write_b32 v2, v4
	v_add_u32_e32 v2, 0x800, v2
	s_andn2_b64 exec, exec, s[8:9]
	s_cbranch_execnz .LBB0_21
	s_or_b64 exec, exec, s[8:9]
	s_mul_hi_i32 s6, s18, 0x38e38e39
	s_waitcnt lgkmcnt(0)
	s_barrier
	s_lshr_b32 s7, s6, 31
	s_ashr_i32 s19, s6, 3
	ds_read_b32 v0, v103
	ds_read_b32 v1, v104
	s_add_i32 s19, s19, s7
	s_mul_i32 s6, s19, 36
	s_sub_i32 s6, s18, s6
	s_lshl_b32 s6, s6, 8
	s_waitcnt lgkmcnt(1)
	v_readfirstlane_b32 s8, v0
	s_waitcnt lgkmcnt(0)
	v_readfirstlane_b32 s9, v1
	s_ashr_i32 s7, s6, 31
	s_mul_i32 s24, s19, 0x2400000
	v_lshl_add_u64 v[0:1], s[8:9], 0, v[88:89]
	s_lshl_b64 s[8:9], s[6:7], 2
	s_mul_hi_i32 s23, s19, 0x2400000
	s_add_u32 s24, s24, s8
	s_addc_u32 s25, s23, s9
	v_lshl_add_u64 v[94:95], v[0:1], 0, s[24:25]
	v_mov_b32_e32 v0, 0
	s_mov_b32 s7, -4
	s_mov_b32 s23, s10
	v_mov_b32_e32 v1, v0
	v_mov_b32_e32 v2, v0
	v_mov_b32_e32 v3, v0
	v_mov_b32_e32 v4, v0
	v_mov_b32_e32 v5, v0
	v_mov_b32_e32 v6, v0
	v_mov_b32_e32 v7, v0
	v_mov_b32_e32 v8, v0
	v_mov_b32_e32 v9, v0
	v_mov_b32_e32 v10, v0
	v_mov_b32_e32 v11, v0
	v_mov_b32_e32 v12, v0
	v_mov_b32_e32 v13, v0
	v_mov_b32_e32 v14, v0
	v_mov_b32_e32 v15, v0
	v_mov_b32_e32 v16, v0
	v_mov_b32_e32 v17, v0
	v_mov_b32_e32 v18, v0
	v_mov_b32_e32 v19, v0
	v_mov_b32_e32 v20, v0
	v_mov_b32_e32 v21, v0
	v_mov_b32_e32 v22, v0
	v_mov_b32_e32 v23, v0
	v_mov_b32_e32 v24, v0
	v_mov_b32_e32 v25, v0
	v_mov_b32_e32 v26, v0
	v_mov_b32_e32 v27, v0
	v_mov_b32_e32 v28, v0
	v_mov_b32_e32 v29, v0
	v_mov_b32_e32 v30, v0
	v_mov_b32_e32 v31, v0
	v_mov_b32_e32 v32, v0
	v_mov_b32_e32 v33, v0
	v_mov_b32_e32 v34, v0
	v_mov_b32_e32 v35, v0
	v_mov_b32_e32 v36, v0
	v_mov_b32_e32 v37, v0
	v_mov_b32_e32 v38, v0
	v_mov_b32_e32 v39, v0
	v_mov_b32_e32 v40, v0
	v_mov_b32_e32 v41, v0
	v_mov_b32_e32 v42, v0
	v_mov_b32_e32 v43, v0
	v_mov_b32_e32 v44, v0
	v_mov_b32_e32 v45, v0
	v_mov_b32_e32 v46, v0
	v_mov_b32_e32 v47, v0
	v_mov_b32_e32 v48, v0
	v_mov_b32_e32 v49, v0
	v_mov_b32_e32 v50, v0
	v_mov_b32_e32 v51, v0
	v_mov_b32_e32 v52, v0
	v_mov_b32_e32 v53, v0
	v_mov_b32_e32 v54, v0
	v_mov_b32_e32 v55, v0
	v_mov_b32_e32 v56, v0
	v_mov_b32_e32 v57, v0
	v_mov_b32_e32 v58, v0
	v_mov_b32_e32 v59, v0
	v_mov_b32_e32 v60, v0
	v_mov_b32_e32 v61, v0
	v_mov_b32_e32 v62, v0
	v_mov_b32_e32 v63, v0
	v_mov_b32_e32 v64, v0
	v_mov_b32_e32 v65, v0
	v_mov_b32_e32 v66, v0
	v_mov_b32_e32 v67, v0
	v_add_co_u32_e32 v198, vcc, s14, v94
	s_nop 1
	v_addc_co_u32_e32 v199, vcc, -1, v95, vcc
	v_add_co_u32_e32 v200, vcc, s15, v94
	s_nop 1
	v_addc_co_u32_e32 v201, vcc, -1, v95, vcc
	v_add_co_u32_e32 v202, vcc, s16, v94
	s_nop 1
	v_addc_co_u32_e32 v203, vcc, -1, v95, vcc
	global_load_dwordx4 v[182:185], v[198:199], off
	global_load_dwordx4 v[186:189], v[200:201], off
	global_load_dwordx4 v[190:193], v[202:203], off
	global_load_dwordx4 v[194:197], v[94:95], off
	v_lshl_add_u64 v[94:95], v[94:95], 0, s[2:3]
.LBB0_23:
	s_waitcnt vmcnt(0)
	v_mov_b32_e32 v68, v182
	v_mov_b32_e32 v69, v183
	v_mov_b32_e32 v70, v184
	v_mov_b32_e32 v71, v185
	v_mov_b32_e32 v76, v186
	v_mov_b32_e32 v77, v187
	v_mov_b32_e32 v78, v188
	v_mov_b32_e32 v79, v189
	v_mov_b32_e32 v80, v190
	v_mov_b32_e32 v81, v191
	v_mov_b32_e32 v82, v192
	v_mov_b32_e32 v83, v193
	v_mov_b32_e32 v72, v194
	v_mov_b32_e32 v73, v195
	v_mov_b32_e32 v74, v196
	v_mov_b32_e32 v75, v197
	v_mov_b32_e32 v118, s23
	s_add_i32 s24, s23, 0x10000
	ds_read_b128 v[110:113], v118
	s_add_i32 s7, s7, 4
	s_add_i32 s23, s23, 16
	s_cmpk_gt_u32 s7, 0x7b
	s_cbranch_scc1 .Lmod_nopf
	v_add_co_u32_e32 v198, vcc, s14, v94
	s_nop 1
	v_addc_co_u32_e32 v199, vcc, -1, v95, vcc
	v_add_co_u32_e32 v200, vcc, s15, v94
	s_nop 1
	v_addc_co_u32_e32 v201, vcc, -1, v95, vcc
	v_add_co_u32_e32 v202, vcc, s16, v94
	s_nop 1
	v_addc_co_u32_e32 v203, vcc, -1, v95, vcc
	global_load_dwordx4 v[182:185], v[198:199], off
	global_load_dwordx4 v[186:189], v[200:201], off
	global_load_dwordx4 v[190:193], v[202:203], off
	global_load_dwordx4 v[194:197], v[94:95], off
	v_lshl_add_u64 v[94:95], v[94:95], 0, s[2:3]
.Lmod_nopf:
	s_waitcnt lgkmcnt(0)
	v_mov_b32_e32 v86, v113
	v_pk_mul_f32 v[114:115], v[78:79], v[110:111] op_sel:[0,1]
	v_pk_mul_f32 v[116:117], v[76:77], v[110:111] op_sel:[0,1]
	v_pk_fma_f32 v[114:115], v[70:71], v[110:111], v[114:115] op_sel_hi:[1,0,1]
	v_pk_fma_f32 v[110:111], v[68:69], v[110:111], v[116:117] op_sel_hi:[1,0,1]
	v_pk_fma_f32 v[114:115], v[82:83], v[112:113], v[114:115] op_sel_hi:[1,0,1]
	v_pk_fma_f32 v[110:111], v[80:81], v[112:113], v[110:111] op_sel_hi:[1,0,1]
	v_pk_fma_f32 v[112:113], v[74:75], v[86:87], v[114:115] op_sel_hi:[1,0,1]
	v_pk_fma_f32 v[110:111], v[72:73], v[86:87], v[110:111] op_sel_hi:[1,0,1]
	v_pk_add_f32 v[66:67], v[66:67], v[112:113]
	v_pk_add_f32 v[64:65], v[64:65], v[110:111]
	ds_read_b128 v[110:113], v118 offset:4096
	s_waitcnt lgkmcnt(0)
	v_pk_mul_f32 v[114:115], v[78:79], v[110:111] op_sel:[0,1]
	v_pk_mul_f32 v[116:117], v[76:77], v[110:111] op_sel:[0,1]
	v_pk_fma_f32 v[114:115], v[70:71], v[110:111], v[114:115] op_sel_hi:[1,0,1]
	v_pk_fma_f32 v[110:111], v[68:69], v[110:111], v[116:117] op_sel_hi:[1,0,1]
	v_pk_fma_f32 v[114:115], v[82:83], v[112:113], v[114:115] op_sel_hi:[1,0,1]
	v_pk_fma_f32 v[110:111], v[80:81], v[112:113], v[110:111] op_sel_hi:[1,0,1]
	v_mov_b32_e32 v86, v113
	v_pk_fma_f32 v[112:113], v[74:75], v[86:87], v[114:115] op_sel_hi:[1,0,1]
	v_pk_fma_f32 v[110:111], v[72:73], v[86:87], v[110:111] op_sel_hi:[1,0,1]
	v_pk_add_f32 v[62:63], v[62:63], v[112:113]
	v_pk_add_f32 v[60:61], v[60:61], v[110:111]
	ds_read_b128 v[110:113], v118 offset:8192
	s_waitcnt lgkmcnt(0)
	v_pk_mul_f32 v[114:115], v[78:79], v[110:111] op_sel:[0,1]
	v_pk_mul_f32 v[116:117], v[76:77], v[110:111] op_sel:[0,1]
	v_pk_fma_f32 v[114:115], v[70:71], v[110:111], v[114:115] op_sel_hi:[1,0,1]
	v_pk_fma_f32 v[110:111], v[68:69], v[110:111], v[116:117] op_sel_hi:[1,0,1]
	v_pk_fma_f32 v[114:115], v[82:83], v[112:113], v[114:115] op_sel_hi:[1,0,1]
	v_pk_fma_f32 v[110:111], v[80:81], v[112:113], v[110:111] op_sel_hi:[1,0,1]
	v_mov_b32_e32 v86, v113
	v_pk_fma_f32 v[112:113], v[74:75], v[86:87], v[114:115] op_sel_hi:[1,0,1]
	v_pk_fma_f32 v[110:111], v[72:73], v[86:87], v[110:111] op_sel_hi:[1,0,1]
	v_pk_add_f32 v[58:59], v[58:59], v[112:113]
	v_pk_add_f32 v[56:57], v[56:57], v[110:111]
	ds_read_b128 v[110:113], v118 offset:12288
	s_waitcnt lgkmcnt(0)
	v_pk_mul_f32 v[114:115], v[78:79], v[110:111] op_sel:[0,1]
	v_pk_mul_f32 v[116:117], v[76:77], v[110:111] op_sel:[0,1]
	v_pk_fma_f32 v[114:115], v[70:71], v[110:111], v[114:115] op_sel_hi:[1,0,1]
	v_pk_fma_f32 v[110:111], v[68:69], v[110:111], v[116:117] op_sel_hi:[1,0,1]
	v_pk_fma_f32 v[114:115], v[82:83], v[112:113], v[114:115] op_sel_hi:[1,0,1]
	v_pk_fma_f32 v[110:111], v[80:81], v[112:113], v[110:111] op_sel_hi:[1,0,1]
	v_mov_b32_e32 v86, v113
	v_pk_fma_f32 v[112:113], v[74:75], v[86:87], v[114:115] op_sel_hi:[1,0,1]
	v_pk_fma_f32 v[110:111], v[72:73], v[86:87], v[110:111] op_sel_hi:[1,0,1]
	v_pk_add_f32 v[54:55], v[54:55], v[112:113]
	v_pk_add_f32 v[52:53], v[52:53], v[110:111]
	ds_read_b128 v[110:113], v118 offset:16384
	s_waitcnt lgkmcnt(0)
	v_pk_mul_f32 v[114:115], v[78:79], v[110:111] op_sel:[0,1]
	v_pk_mul_f32 v[116:117], v[76:77], v[110:111] op_sel:[0,1]
	v_pk_fma_f32 v[114:115], v[70:71], v[110:111], v[114:115] op_sel_hi:[1,0,1]
	v_pk_fma_f32 v[110:111], v[68:69], v[110:111], v[116:117] op_sel_hi:[1,0,1]
	v_pk_fma_f32 v[114:115], v[82:83], v[112:113], v[114:115] op_sel_hi:[1,0,1]
	v_pk_fma_f32 v[110:111], v[80:81], v[112:113], v[110:111] op_sel_hi:[1,0,1]
	v_mov_b32_e32 v86, v113
	v_pk_fma_f32 v[112:113], v[74:75], v[86:87], v[114:115] op_sel_hi:[1,0,1]
	v_pk_fma_f32 v[110:111], v[72:73], v[86:87], v[110:111] op_sel_hi:[1,0,1]
	v_pk_add_f32 v[50:51], v[50:51], v[112:113]
	v_pk_add_f32 v[48:49], v[48:49], v[110:111]
	ds_read_b128 v[110:113], v118 offset:20480
	s_waitcnt lgkmcnt(0)
	v_pk_mul_f32 v[114:115], v[78:79], v[110:111] op_sel:[0,1]
	v_pk_mul_f32 v[116:117], v[76:77], v[110:111] op_sel:[0,1]
	v_pk_fma_f32 v[114:115], v[70:71], v[110:111], v[114:115] op_sel_hi:[1,0,1]
	v_pk_fma_f32 v[110:111], v[68:69], v[110:111], v[116:117] op_sel_hi:[1,0,1]
	v_pk_fma_f32 v[114:115], v[82:83], v[112:113], v[114:115] op_sel_hi:[1,0,1]
	v_pk_fma_f32 v[110:111], v[80:81], v[112:113], v[110:111] op_sel_hi:[1,0,1]
	v_mov_b32_e32 v86, v113
	v_pk_fma_f32 v[112:113], v[74:75], v[86:87], v[114:115] op_sel_hi:[1,0,1]
	v_pk_fma_f32 v[110:111], v[72:73], v[86:87], v[110:111] op_sel_hi:[1,0,1]
	v_pk_add_f32 v[46:47], v[46:47], v[112:113]
	v_pk_add_f32 v[44:45], v[44:45], v[110:111]
	ds_read_b128 v[110:113], v118 offset:24576
	s_waitcnt lgkmcnt(0)
	v_pk_mul_f32 v[114:115], v[78:79], v[110:111] op_sel:[0,1]
	v_pk_mul_f32 v[116:117], v[76:77], v[110:111] op_sel:[0,1]
	v_pk_fma_f32 v[114:115], v[70:71], v[110:111], v[114:115] op_sel_hi:[1,0,1]
	v_pk_fma_f32 v[110:111], v[68:69], v[110:111], v[116:117] op_sel_hi:[1,0,1]
	v_pk_fma_f32 v[114:115], v[82:83], v[112:113], v[114:115] op_sel_hi:[1,0,1]
	v_pk_fma_f32 v[110:111], v[80:81], v[112:113], v[110:111] op_sel_hi:[1,0,1]
	v_mov_b32_e32 v86, v113
	v_pk_fma_f32 v[112:113], v[74:75], v[86:87], v[114:115] op_sel_hi:[1,0,1]
	v_pk_fma_f32 v[110:111], v[72:73], v[86:87], v[110:111] op_sel_hi:[1,0,1]
	v_pk_add_f32 v[42:43], v[42:43], v[112:113]
	v_pk_add_f32 v[40:41], v[40:41], v[110:111]
	ds_read_b128 v[110:113], v118 offset:28672
	s_waitcnt lgkmcnt(0)
	v_pk_mul_f32 v[114:115], v[78:79], v[110:111] op_sel:[0,1]
	v_pk_mul_f32 v[116:117], v[76:77], v[110:111] op_sel:[0,1]
	v_pk_fma_f32 v[114:115], v[70:71], v[110:111], v[114:115] op_sel_hi:[1,0,1]
	v_pk_fma_f32 v[110:111], v[68:69], v[110:111], v[116:117] op_sel_hi:[1,0,1]
	v_pk_fma_f32 v[114:115], v[82:83], v[112:113], v[114:115] op_sel_hi:[1,0,1]
	v_pk_fma_f32 v[110:111], v[80:81], v[112:113], v[110:111] op_sel_hi:[1,0,1]
	v_mov_b32_e32 v86, v113
	v_pk_fma_f32 v[112:113], v[74:75], v[86:87], v[114:115] op_sel_hi:[1,0,1]
	v_pk_fma_f32 v[110:111], v[72:73], v[86:87], v[110:111] op_sel_hi:[1,0,1]
	v_pk_add_f32 v[38:39], v[38:39], v[112:113]
	v_pk_add_f32 v[36:37], v[36:37], v[110:111]
	ds_read_b128 v[110:113], v118 offset:32768
	s_waitcnt lgkmcnt(0)
	v_pk_mul_f32 v[114:115], v[78:79], v[110:111] op_sel:[0,1]
	v_pk_mul_f32 v[116:117], v[76:77], v[110:111] op_sel:[0,1]
	v_pk_fma_f32 v[114:115], v[70:71], v[110:111], v[114:115] op_sel_hi:[1,0,1]
	v_pk_fma_f32 v[110:111], v[68:69], v[110:111], v[116:117] op_sel_hi:[1,0,1]
	v_pk_fma_f32 v[114:115], v[82:83], v[112:113], v[114:115] op_sel_hi:[1,0,1]
	v_pk_fma_f32 v[110:111], v[80:81], v[112:113], v[110:111] op_sel_hi:[1,0,1]
	v_mov_b32_e32 v86, v113
	v_pk_fma_f32 v[112:113], v[74:75], v[86:87], v[114:115] op_sel_hi:[1,0,1]
	v_pk_fma_f32 v[110:111], v[72:73], v[86:87], v[110:111] op_sel_hi:[1,0,1]
	v_pk_add_f32 v[34:35], v[34:35], v[112:113]
	v_pk_add_f32 v[32:33], v[32:33], v[110:111]
	ds_read_b128 v[110:113], v118 offset:36864
	s_waitcnt lgkmcnt(0)
	v_pk_mul_f32 v[114:115], v[78:79], v[110:111] op_sel:[0,1]
	v_pk_mul_f32 v[116:117], v[76:77], v[110:111] op_sel:[0,1]
	v_pk_fma_f32 v[114:115], v[70:71], v[110:111], v[114:115] op_sel_hi:[1,0,1]
	v_pk_fma_f32 v[110:111], v[68:69], v[110:111], v[116:117] op_sel_hi:[1,0,1]
	v_pk_fma_f32 v[114:115], v[82:83], v[112:113], v[114:115] op_sel_hi:[1,0,1]
	v_pk_fma_f32 v[110:111], v[80:81], v[112:113], v[110:111] op_sel_hi:[1,0,1]
	v_mov_b32_e32 v86, v113
	v_pk_fma_f32 v[112:113], v[74:75], v[86:87], v[114:115] op_sel_hi:[1,0,1]
	v_pk_fma_f32 v[110:111], v[72:73], v[86:87], v[110:111] op_sel_hi:[1,0,1]
	v_pk_add_f32 v[30:31], v[30:31], v[112:113]
	v_pk_add_f32 v[28:29], v[28:29], v[110:111]
	ds_read_b128 v[110:113], v118 offset:40960
	s_waitcnt lgkmcnt(0)
	v_pk_mul_f32 v[114:115], v[78:79], v[110:111] op_sel:[0,1]
	v_pk_mul_f32 v[116:117], v[76:77], v[110:111] op_sel:[0,1]
	v_pk_fma_f32 v[114:115], v[70:71], v[110:111], v[114:115] op_sel_hi:[1,0,1]
	v_pk_fma_f32 v[110:111], v[68:69], v[110:111], v[116:117] op_sel_hi:[1,0,1]
	v_pk_fma_f32 v[114:115], v[82:83], v[112:113], v[114:115] op_sel_hi:[1,0,1]
	v_pk_fma_f32 v[110:111], v[80:81], v[112:113], v[110:111] op_sel_hi:[1,0,1]
	v_mov_b32_e32 v86, v113
	v_pk_fma_f32 v[112:113], v[74:75], v[86:87], v[114:115] op_sel_hi:[1,0,1]
	v_pk_fma_f32 v[110:111], v[72:73], v[86:87], v[110:111] op_sel_hi:[1,0,1]
	v_pk_add_f32 v[26:27], v[26:27], v[112:113]
	v_pk_add_f32 v[24:25], v[24:25], v[110:111]
	ds_read_b128 v[110:113], v118 offset:45056
	s_waitcnt lgkmcnt(0)
	v_pk_mul_f32 v[114:115], v[78:79], v[110:111] op_sel:[0,1]
	v_pk_mul_f32 v[116:117], v[76:77], v[110:111] op_sel:[0,1]
	v_pk_fma_f32 v[114:115], v[70:71], v[110:111], v[114:115] op_sel_hi:[1,0,1]
	v_pk_fma_f32 v[110:111], v[68:69], v[110:111], v[116:117] op_sel_hi:[1,0,1]
	v_pk_fma_f32 v[114:115], v[82:83], v[112:113], v[114:115] op_sel_hi:[1,0,1]
	v_pk_fma_f32 v[110:111], v[80:81], v[112:113], v[110:111] op_sel_hi:[1,0,1]
	v_mov_b32_e32 v86, v113
	v_pk_fma_f32 v[112:113], v[74:75], v[86:87], v[114:115] op_sel_hi:[1,0,1]
	v_pk_fma_f32 v[110:111], v[72:73], v[86:87], v[110:111] op_sel_hi:[1,0,1]
	v_pk_add_f32 v[22:23], v[22:23], v[112:113]
	v_pk_add_f32 v[20:21], v[20:21], v[110:111]
	ds_read_b128 v[110:113], v118 offset:49152
	s_waitcnt lgkmcnt(0)
	v_pk_mul_f32 v[114:115], v[78:79], v[110:111] op_sel:[0,1]
	v_pk_mul_f32 v[116:117], v[76:77], v[110:111] op_sel:[0,1]
	v_pk_fma_f32 v[114:115], v[70:71], v[110:111], v[114:115] op_sel_hi:[1,0,1]
	v_pk_fma_f32 v[110:111], v[68:69], v[110:111], v[116:117] op_sel_hi:[1,0,1]
	v_pk_fma_f32 v[114:115], v[82:83], v[112:113], v[114:115] op_sel_hi:[1,0,1]
	v_pk_fma_f32 v[110:111], v[80:81], v[112:113], v[110:111] op_sel_hi:[1,0,1]
	v_mov_b32_e32 v86, v113
	v_pk_fma_f32 v[112:113], v[74:75], v[86:87], v[114:115] op_sel_hi:[1,0,1]
	v_pk_fma_f32 v[110:111], v[72:73], v[86:87], v[110:111] op_sel_hi:[1,0,1]
	v_pk_add_f32 v[18:19], v[18:19], v[112:113]
	v_pk_add_f32 v[16:17], v[16:17], v[110:111]
	ds_read_b128 v[110:113], v118 offset:53248
	s_waitcnt lgkmcnt(0)
	v_pk_mul_f32 v[114:115], v[78:79], v[110:111] op_sel:[0,1]
	v_pk_mul_f32 v[116:117], v[76:77], v[110:111] op_sel:[0,1]
	v_pk_fma_f32 v[114:115], v[70:71], v[110:111], v[114:115] op_sel_hi:[1,0,1]
	v_pk_fma_f32 v[110:111], v[68:69], v[110:111], v[116:117] op_sel_hi:[1,0,1]
	v_pk_fma_f32 v[114:115], v[82:83], v[112:113], v[114:115] op_sel_hi:[1,0,1]
	v_pk_fma_f32 v[110:111], v[80:81], v[112:113], v[110:111] op_sel_hi:[1,0,1]
	v_mov_b32_e32 v86, v113
	v_pk_fma_f32 v[112:113], v[74:75], v[86:87], v[114:115] op_sel_hi:[1,0,1]
	v_pk_fma_f32 v[110:111], v[72:73], v[86:87], v[110:111] op_sel_hi:[1,0,1]
	v_pk_add_f32 v[14:15], v[14:15], v[112:113]
	v_pk_add_f32 v[12:13], v[12:13], v[110:111]
	ds_read_b128 v[110:113], v118 offset:57344
	s_waitcnt lgkmcnt(0)
	v_pk_mul_f32 v[114:115], v[78:79], v[110:111] op_sel:[0,1]
	v_pk_mul_f32 v[116:117], v[76:77], v[110:111] op_sel:[0,1]
	v_pk_fma_f32 v[114:115], v[70:71], v[110:111], v[114:115] op_sel_hi:[1,0,1]
	v_pk_fma_f32 v[110:111], v[68:69], v[110:111], v[116:117] op_sel_hi:[1,0,1]
	v_pk_fma_f32 v[114:115], v[82:83], v[112:113], v[114:115] op_sel_hi:[1,0,1]
	v_pk_fma_f32 v[110:111], v[80:81], v[112:113], v[110:111] op_sel_hi:[1,0,1]
	v_mov_b32_e32 v86, v113
	v_pk_fma_f32 v[112:113], v[74:75], v[86:87], v[114:115] op_sel_hi:[1,0,1]
	v_pk_fma_f32 v[110:111], v[72:73], v[86:87], v[110:111] op_sel_hi:[1,0,1]
	v_pk_add_f32 v[10:11], v[10:11], v[112:113]
	v_pk_add_f32 v[8:9], v[8:9], v[110:111]
	ds_read_b128 v[110:113], v118 offset:61440
	s_waitcnt lgkmcnt(0)
	v_pk_mul_f32 v[114:115], v[78:79], v[110:111] op_sel:[0,1]
	v_pk_mul_f32 v[116:117], v[76:77], v[110:111] op_sel:[0,1]
	v_pk_fma_f32 v[114:115], v[70:71], v[110:111], v[114:115] op_sel_hi:[1,0,1]
	v_pk_fma_f32 v[110:111], v[68:69], v[110:111], v[116:117] op_sel_hi:[1,0,1]
	v_pk_fma_f32 v[114:115], v[82:83], v[112:113], v[114:115] op_sel_hi:[1,0,1]
	v_pk_fma_f32 v[110:111], v[80:81], v[112:113], v[110:111] op_sel_hi:[1,0,1]
	v_mov_b32_e32 v86, v113
	v_pk_fma_f32 v[112:113], v[74:75], v[86:87], v[114:115] op_sel_hi:[1,0,1]
	v_pk_fma_f32 v[110:111], v[72:73], v[86:87], v[110:111] op_sel_hi:[1,0,1]
	v_mov_b32_e32 v86, s24
	v_pk_add_f32 v[6:7], v[6:7], v[112:113]
	v_pk_add_f32 v[4:5], v[4:5], v[110:111]
	ds_read_b128 v[110:113], v86
	s_waitcnt lgkmcnt(0)
	v_pk_mul_f32 v[78:79], v[78:79], v[110:111] op_sel:[0,1]
	v_pk_mul_f32 v[76:77], v[76:77], v[110:111] op_sel:[0,1]
	v_pk_fma_f32 v[70:71], v[70:71], v[110:111], v[78:79] op_sel_hi:[1,0,1]
	v_pk_fma_f32 v[68:69], v[68:69], v[110:111], v[76:77] op_sel_hi:[1,0,1]
	v_pk_fma_f32 v[70:71], v[82:83], v[112:113], v[70:71] op_sel_hi:[1,0,1]
	v_pk_fma_f32 v[68:69], v[80:81], v[112:113], v[68:69] op_sel_hi:[1,0,1]
	v_mov_b32_e32 v76, v113
	v_pk_fma_f32 v[70:71], v[74:75], v[76:77], v[70:71] op_sel_hi:[1,0,1]
	v_pk_fma_f32 v[68:69], v[72:73], v[76:77], v[68:69] op_sel_hi:[1,0,1]
	v_pk_add_f32 v[2:3], v[2:3], v[70:71]
	v_pk_add_f32 v[0:1], v[0:1], v[68:69]
	s_cbranch_scc0 .LBB0_23
	s_barrier
	ds_write_b128 v105, v[64:67]
	ds_write_b128 v105, v[60:63] offset:1024
	ds_write_b128 v105, v[56:59] offset:2048
	ds_write_b128 v105, v[52:55] offset:3072
	ds_write_b128 v105, v[48:51] offset:4096
	ds_write_b128 v105, v[44:47] offset:5120
	ds_write_b128 v105, v[40:43] offset:6144
	ds_write_b128 v105, v[36:39] offset:7168
	ds_write_b128 v105, v[32:35] offset:8192
	ds_write_b128 v105, v[28:31] offset:9216
	ds_write_b128 v105, v[24:27] offset:10240
	ds_write_b128 v105, v[20:23] offset:11264
	ds_write_b128 v105, v[16:19] offset:12288
	ds_write_b128 v105, v[12:15] offset:13312
	ds_write_b128 v105, v[8:11] offset:14336
	ds_write_b128 v105, v[4:7] offset:15360
	ds_write_b128 v105, v[0:3] offset:16384
	s_waitcnt lgkmcnt(0)
	s_barrier
	ds_read_b32 v0, v106
	ds_read_b32 v1, v107
	ds_read_b32 v2, v108
	ds_read_b32 v3, v109
	v_mov_b64_e32 v[6:7], s[8:9]
	s_waitcnt lgkmcnt(3)
	v_readfirstlane_b32 s24, v0
	s_waitcnt lgkmcnt(2)
	v_readfirstlane_b32 s25, v1
	s_waitcnt lgkmcnt(1)
	v_readfirstlane_b32 s7, v2
	s_waitcnt lgkmcnt(0)
	v_readfirstlane_b32 s23, v3
	v_mov_b32_e32 v0, s7
	s_mul_i32 s7, s19, 0x2400
	s_add_i32 s7, s7, s6
	v_or_b32_sdwa v2, s7, v181 dst_sel:DWORD dst_unused:UNUSED_PAD src0_sel:DWORD src1_sel:BYTE_0
	v_mov_b32_e32 v1, s23
	v_ashrrev_i32_e32 v3, 31, v2
	v_mad_u64_u32 v[4:5], s[6:7], s19, 17, v[92:93]
	v_lshl_add_u64 v[0:1], v[2:3], 2, v[0:1]
	v_lshl_add_u64 v[2:3], s[24:25], 0, v[90:91]
	v_mad_i64_i32 v[4:5], s[6:7], v4, s11, v[6:7]
	v_lshl_add_u64 v[2:3], v[2:3], 0, v[4:5]
	s_mov_b64 s[6:7], 0
	v_mov_b32_e32 v4, v98
	v_mov_b32_e32 v5, v97
